# adaLN GEMV items spread over all 256 workgroups (6 waves each); nt loads in qkv-prep/conv loops; barrier poll sleep 2
# baseline (speedup 1.0000x reference)
.LBB0_9:
	s_sleep 2
	global_load_dword v2, v1, s[4:5] offset:32 sc1
	s_waitcnt vmcnt(0)
	v_and_b32_e32 v2, 0xffff0000, v2
	v_cmp_ne_u32_e32 vcc, v2, v0
	s_or_b64 s[6:7], vcc, s[6:7]
	s_andn2_b64 exec, exec, s[6:7]
	s_cbranch_execnz .LBB0_9

.LBB0_29:
	s_mov_b64 s[54:55], 0
	s_load_dword s12, s[90:91], 0xd8
	v_mbcnt_lo_u32_b32 v0, -1, 0
	v_mbcnt_hi_u32_b32 v0, -1, v0
	s_mov_b32 s0, s88
	v_or_b32_e32 v76, s94, v0
	s_waitcnt lgkmcnt(0)
	s_mov_b32 s1, s12
	v_mov_b32_e32 v1, v76
	s_mov_b32 s0, s88
	v_ashrrev_i32_e32 v2, 6, v1
	s_add_u32 s56, s86, s54
	s_movk_i32 s1, 0x600
	s_mul_i32 s98, s0, 6
	v_add_u32_e32 v38, s98, v2
	v_mov_b32_e32 v3, 0x600
	v_cmp_gt_u32_e32 vcc, 6, v2
	s_nop 1
	v_cndmask_b32_e32 v38, v3, v38, vcc
	s_mov_b64 s[4:5], 0
	s_addc_u32 s57, s87, s55
	s_mov_b32 s0, s12
	v_cmp_gt_i32_e32 vcc, s1, v38
	s_and_saveexec_b64 s[6:7], vcc
	s_cbranch_execz .LBB0_36
	v_bfe_u32 v6, v1, 2, 4
	v_lshlrev_b32_e32 v1, 2, v1
	v_and_b32_e32 v39, 12, v1
	v_and_b32_e32 v1, 64, v0
	v_add_u32_e32 v1, 64, v1
	v_xor_b32_e32 v4, 4, v0
	v_cmp_lt_i32_e32 vcc, v4, v1
	s_load_dwordx16 s[16:31], s[90:91], 0x0
	s_lshl_b64 s[8:9], s[54:55], 2
	v_cndmask_b32_e32 v4, v0, v4, vcc
	v_lshlrev_b32_e32 v40, 2, v4
	v_xor_b32_e32 v4, 8, v0
	v_cmp_lt_i32_e32 vcc, v4, v1
	s_waitcnt lgkmcnt(0)
	v_mov_b32_e32 v2, s24
	v_mov_b32_e32 v3, s25
	v_cndmask_b32_e32 v4, v0, v4, vcc
	v_lshlrev_b32_e32 v41, 2, v4
	v_xor_b32_e32 v4, 16, v0
	v_cmp_lt_i32_e32 vcc, v4, v1
	s_mov_b32 s1, 0xc000
	s_add_u32 s10, s26, s8
	v_cndmask_b32_e32 v4, v0, v4, vcc
	v_lshlrev_b32_e32 v42, 2, v4
	v_xor_b32_e32 v4, 32, v0
	v_cmp_lt_i32_e32 vcc, v4, v1
	v_cmp_eq_u32_e64 s[2:3], 0, v6
	v_mov_b32_e32 v7, 0
	v_cndmask_b32_e32 v0, v0, v4, vcc
	v_mad_u64_u32 v[4:5], s[14:15], v6, s1, v[2:3]
	v_lshlrev_b32_e32 v6, 2, v6
	s_addc_u32 s11, s27, s9
	s_lshl_b32 s0, s0, 3
	v_lshlrev_b32_e32 v43, 2, v0
	v_lshl_add_u64 v[8:9], s[18:19], 0, v[6:7]
	v_lshl_add_u64 v[10:11], s[22:23], 0, v[6:7]
	s_mov_b32 s13, 0x2aaaaaab
	s_mov_b32 s14, 0x6000000
	s_movk_i32 s15, 0x2000
	s_mov_b32 s16, 0xc0000
	s_mov_b32 s17, 0x180000
	s_mov_b32 s20, 0x240000
	s_mov_b32 s21, 0x300000
	s_mov_b32 s26, 0x3c0000
	s_mov_b32 s27, 0x480000
	s_mov_b32 s28, 0x540000
	s_mov_b64 s[18:19], 0x600000
	s_mov_b64 s[22:23], 0x200
	s_movk_i32 s29, 0x5ff
	s_branch .LBB0_32

.LBB0_115:
	s_or_b64 exec, exec, s[2:3]
	s_abs_i32 s15, s12
	v_cvt_f32_u32_e32 v2, s15
	v_lshlrev_b32_e32 v0, 2, v76
	v_and_b32_e32 v82, 60, v0
	s_sub_i32 s2, 0, s15
	v_rcp_iflag_f32_e32 v0, v2
	s_mov_b32 s13, s88
	s_add_i32 s14, s13, s12
	v_mul_f32_e32 v0, 0x4f7ffffe, v0
	v_cvt_u32_f32_e32 v0, v0
	s_abs_i32 s1, s14
	s_ashr_i32 s0, s14, 31
	v_ashrrev_i32_e32 v78, 3, v76
	v_readfirstlane_b32 s16, v0
	s_mul_i32 s2, s2, s16
	s_mul_hi_u32 s2, s16, s2
	s_add_i32 s16, s16, s2
	s_mul_hi_u32 s2, s1, s16
	s_mul_i32 s2, s2, s15
	s_sub_i32 s1, s1, s2
	s_sub_i32 s2, s1, s15
	s_cmp_ge_u32 s1, s15
	s_cselect_b32 s1, s2, s1
	s_sub_i32 s2, s1, s15
	s_cmp_ge_u32 s1, s15
	s_cselect_b32 s1, s2, s1
	s_xor_b32 s1, s1, s0
	v_lshlrev_b32_e32 v2, 3, v76
	s_sub_i32 s17, s1, s0
	v_ashrrev_i32_e32 v77, 4, v76
	v_mov_b32_e32 v1, 0
	v_lshl_add_u32 v79, v82, 2, 0
	v_and_b32_e32 v80, 56, v2
	s_cmpk_lt_i32 s17, 0x480
	v_lshl_add_u32 v81, v78, 2, 0
	s_load_dword s59, s[90:91], 0xd8
	v_mbcnt_lo_u32_b32 v100, -1, 0
	v_mbcnt_hi_u32_b32 v100, -1, v100
	s_lshr_b32 s69, s94, 6
	s_lshl_b32 s82, s69, 10
	s_lshl_b32 s83, s69, 1
	s_lshr_b32 s98, s69, 2
	v_lshrrev_b32_e32 v101, 5, v100
	v_and_b32_e32 v113, 31, v100
	s_add_i32 s70, s83, 0
	v_add_u32_e32 v102, s70, v101
	s_add_i32 s70, s98, 0
	v_xor_b32_e32 v106, s70, v113
	v_lshlrev_b32_e32 v106, 4, v106
	s_add_i32 s70, s83, 16
	v_add_u32_e32 v103, s70, v101
	s_add_i32 s70, s98, 2
	v_xor_b32_e32 v107, s70, v113
	v_lshlrev_b32_e32 v107, 4, v107
	s_add_i32 s70, s83, 32
	v_add_u32_e32 v104, s70, v101
	s_add_i32 s70, s98, 4
	v_xor_b32_e32 v108, s70, v113
	v_lshlrev_b32_e32 v108, 4, v108
	s_add_i32 s70, s83, 48
	v_add_u32_e32 v105, s70, v101
	s_add_i32 s70, s98, 6
	v_xor_b32_e32 v109, s70, v113
	v_lshlrev_b32_e32 v109, 4, v109
	s_lshr_b32 s70, s94, 3
	v_lshrrev_b32_e32 v112, 3, v100
	v_add_u32_e32 v112, s70, v112
	v_and_b32_e32 v101, 7, v100
	v_lshlrev_b32_e32 v111, 4, v101
	v_lshrrev_b32_e32 v113, 2, v112
	v_xor_b32_e32 v113, v113, v101
	v_lshlrev_b32_e32 v113, 4, v113
	v_lshl_add_u32 v110, v101, 12, v113
	v_and_b32_e32 v113, 3, v112
	v_lshl_add_u32 v110, v113, 2, v110
	s_waitcnt lgkmcnt(0)
	s_mov_b32 s61, s88
	s_mov_b32 s60, s88
	s_mov_b32 s101, 7520
	s_mov_b32 s58, -2
.Lwp0_loop:
	s_cmp_lt_i32 s58, 0
	s_cbranch_scc1 .Lwp0_doissue
	s_cmp_lt_u32 s61, s101
	s_cbranch_scc0 .Lwp0_end
	s_cmp_lt_u32 s60, s101
	s_cbranch_scc0 .Lwp0_w0
	s_cmp_eq_u32 s58, 0
	s_cbranch_scc1 .Lwp0_wt0
	s_waitcnt vmcnt(6)
	s_branch .Lwp0_wd

.Lwp0_doissue:
	s_cmp_lt_u32 s60, s101
	s_cbranch_scc0 .Lwp0_noissue
	s_add_u32 s99, s58, 2
	s_and_b32 s99, s99, 3
	s_cmp_lt_u32 s60, 2272
	s_cbranch_scc0 .Lwp0_isel_m_1
	v_readlane_b32 s62, v245, 0
	v_readlane_b32 s63, v245, 1
	s_sub_u32 s65, s60, 0
	s_mov_b32 s64, 0x8d00
	s_mul_hi_u32 s66, s65, 0x39b0ad2
	s_mul_i32 s69, s66, 71
	s_sub_u32 s67, s65, s69
	s_cmp_eq_u32 s67, 70
	s_cselect_b32 s68, 1, 0
	s_branch .Lwp0_isel_done_m

.LBB0_255:
	s_sleep 2
	global_load_dword v1, v0, s[8:9] sc1
	s_waitcnt vmcnt(0)
	v_cmp_gt_u32_e32 vcc, s0, v1
	s_cbranch_vccnz .LBB0_255

.LBB0_273:
	s_sleep 2
	global_load_dword v1, v0, s[6:7] sc1
	s_waitcnt vmcnt(0)
	v_cmp_gt_u32_e32 vcc, s0, v1
	s_cbranch_vccnz .LBB0_273

.LBB0_383:
	s_or_b64 exec, exec, s[22:23]
	v_lshl_add_u64 v[6:7], v[6:7], 0, v[2:3]
	global_load_dwordx4 v[26:29], v[6:7], off offset:3712 nt
	v_ashrrev_i32_e32 v5, 31, v4
	v_lshlrev_b64 v[4:5], 12, v[4:5]
	v_add_u32_e32 v20, s0, v20
	v_lshl_add_u64 v[4:5], s[4:5], 0, v[4:5]
	v_cmp_lt_i32_e32 vcc, s15, v20
	v_lshl_add_u64 v[4:5], v[4:5], 0, v[2:3]
	s_or_b64 s[18:19], vcc, s[18:19]
	v_add_co_u32_e32 v14, vcc, 0x1b3b4000, v4
	v_add_u32_e32 v21, s1, v21
	s_nop 0
	v_addc_co_u32_e32 v15, vcc, 0, v5, vcc
	s_waitcnt vmcnt(0)
	v_and_b32_e32 v4, 0xffff0000, v26
	v_lshlrev_b32_e32 v5, 16, v27
	v_and_b32_e32 v6, 0xffff0000, v27
	v_lshlrev_b32_e32 v7, 16, v28
	v_lshlrev_b32_e32 v2, 16, v26
	v_and_b32_e32 v18, 0xffff0000, v28
	v_lshlrev_b32_e32 v19, 16, v29
	v_and_b32_e32 v26, 0xffff0000, v29
	v_mul_f32_e32 v4, v9, v4
	v_mul_f32_e32 v5, v10, v5
	v_mul_f32_e32 v6, v11, v6
	v_mul_f32_e32 v7, v12, v7
	v_mul_f32_e32 v2, v8, v2
	v_mul_f32_e32 v8, v13, v18
	v_mul_f32_e32 v9, v16, v19
	v_mul_f32_e32 v10, v17, v26
	v_cvt_pk_bf16_f32 v4, v2, v4
	v_cvt_pk_bf16_f32 v5, v5, v6
	v_cvt_pk_bf16_f32 v6, v7, v8
	v_cvt_pk_bf16_f32 v7, v9, v10
	global_store_dwordx4 v[14:15], v[4:7], off offset:512
	s_andn2_b64 exec, exec, s[18:19]
	s_cbranch_execz .LBB0_390
.LBB0_384:
	v_ashrrev_i32_e32 v4, 6, v20
	v_cmp_gt_i32_e32 vcc, s12, v4
	v_and_b32_e32 v8, 0x1f8, v21
	v_mad_i64_i32 v[6:7], s[16:17], v4, s14, v[0:1]
	v_cndmask_b32_e32 v2, v22, v23, vcc
	v_and_b32_e32 v26, v2, v4
	v_lshlrev_b32_e32 v2, 2, v8
	v_cndmask_b32_e32 v5, v24, v25, vcc
	v_lshl_add_u64 v[14:15], s[6:7], 0, v[2:3]
	v_add_u32_e32 v2, -1, v26
	v_cmp_lt_u32_e32 vcc, v2, v5
	v_lshlrev_b32_e32 v2, 1, v8
	v_mov_b32_e32 v18, 0
	v_mov_b32_e32 v19, 0
	v_mov_b32_e32 v8, 0
	v_mov_b32_e32 v9, 0
	v_mov_b32_e32 v10, 0
	v_mov_b32_e32 v11, 0
	v_mov_b32_e32 v12, 0
	v_mov_b32_e32 v13, 0
	v_mov_b32_e32 v16, 0
	v_mov_b32_e32 v17, 0
	s_and_saveexec_b64 s[22:23], vcc
	s_cbranch_execz .LBB0_386
	v_lshl_add_u64 v[8:9], v[6:7], 0, v[2:3]
	v_add_co_u32_e32 v12, vcc, 0xffffd000, v8
	s_nop 1
	v_addc_co_u32_e32 v13, vcc, -1, v9, vcc
	global_load_dwordx4 v[8:11], v[12:13], off offset:-3456 nt
	global_load_dwordx4 v[16:19], v[12:13], off offset:-1408 nt
	global_load_dwordx4 v[28:31], v[14:15], off nt
	global_load_dwordx4 v[32:35], v[14:15], off offset:16 nt
	s_waitcnt vmcnt(0)
	v_lshlrev_b32_e32 v12, 16, v8
	v_and_b32_e32 v13, 0xffff0000, v8
	v_lshlrev_b32_e32 v8, 16, v9
	v_and_b32_e32 v9, 0xffff0000, v9
	v_lshlrev_b32_e32 v38, 16, v10
	v_and_b32_e32 v39, 0xffff0000, v10
	v_lshlrev_b32_e32 v10, 16, v11
	v_and_b32_e32 v11, 0xffff0000, v11
	v_lshlrev_b32_e32 v40, 16, v18
	v_and_b32_e32 v41, 0xffff0000, v18
	v_lshlrev_b32_e32 v18, 16, v19
	v_and_b32_e32 v19, 0xffff0000, v19
	v_pk_mul_f32 v[12:13], v[28:29], v[12:13]
	v_pk_mul_f32 v[28:29], v[30:31], v[8:9]
	v_pk_mul_f32 v[30:31], v[32:33], v[38:39]
	v_pk_mul_f32 v[32:33], v[34:35], v[10:11]
	v_lshlrev_b32_e32 v36, 16, v16
	v_and_b32_e32 v37, 0xffff0000, v16
	v_lshlrev_b32_e32 v16, 16, v17
	v_and_b32_e32 v17, 0xffff0000, v17
	v_pk_fma_f32 v[18:19], v[32:33], v[18:19], 0 op_sel_hi:[1,1,0]
	v_pk_fma_f32 v[8:9], v[12:13], v[36:37], 0 op_sel_hi:[1,1,0]
	v_pk_fma_f32 v[10:11], v[28:29], v[16:17], 0 op_sel_hi:[1,1,0]
	v_pk_fma_f32 v[12:13], v[30:31], v[40:41], 0 op_sel_hi:[1,1,0]
	v_mov_b32_e32 v16, v18
	v_mov_b32_e32 v17, v19
.LBB0_386:
	s_or_b64 exec, exec, s[22:23]
	v_cmp_lt_u32_e32 vcc, v26, v5
	s_and_saveexec_b64 s[22:23], vcc
	s_cbranch_execz .LBB0_388
	v_lshl_add_u64 v[16:17], v[6:7], 0, v[2:3]
	global_load_dwordx4 v[28:31], v[16:17], off offset:2688 nt
	global_load_dwordx4 v[32:35], v[14:15], off offset:2064 nt
	global_load_dwordx4 v[36:39], v[14:15], off offset:2048 nt
	v_add_co_u32_e32 v16, vcc, 0x1000, v16
	s_waitcnt vmcnt(0)
	v_lshlrev_b32_e32 v44, 16, v30
	v_addc_co_u32_e32 v17, vcc, 0, v17, vcc
	global_load_dwordx4 v[40:43], v[16:17], off offset:640 nt
	v_lshlrev_b32_e32 v16, 16, v28
	v_and_b32_e32 v17, 0xffff0000, v28
	v_lshlrev_b32_e32 v28, 16, v29
	v_and_b32_e32 v29, 0xffff0000, v29
	v_and_b32_e32 v45, 0xffff0000, v30
	v_lshlrev_b32_e32 v30, 16, v31
	v_and_b32_e32 v31, 0xffff0000, v31
	v_pk_mul_f32 v[16:17], v[36:37], v[16:17]
	v_pk_mul_f32 v[28:29], v[38:39], v[28:29]
	v_pk_mul_f32 v[32:33], v[32:33], v[44:45]
	v_pk_mul_f32 v[30:31], v[34:35], v[30:31]
	s_waitcnt vmcnt(0)
	v_lshlrev_b32_e32 v34, 16, v40
	v_and_b32_e32 v35, 0xffff0000, v40
	v_lshlrev_b32_e32 v36, 16, v41
	v_and_b32_e32 v37, 0xffff0000, v41
	v_lshlrev_b32_e32 v38, 16, v42
	v_and_b32_e32 v39, 0xffff0000, v42
	v_lshlrev_b32_e32 v40, 16, v43
	v_and_b32_e32 v41, 0xffff0000, v43
	v_pk_fma_f32 v[8:9], v[16:17], v[34:35], v[8:9]
	v_pk_fma_f32 v[10:11], v[28:29], v[36:37], v[10:11]
	v_pk_fma_f32 v[12:13], v[32:33], v[38:39], v[12:13]
	v_pk_fma_f32 v[16:17], v[30:31], v[40:41], v[18:19]
.LBB0_388:
	s_or_b64 exec, exec, s[22:23]
	v_add_u32_e32 v18, 1, v26
	v_cmp_lt_u32_e32 vcc, v18, v5
	s_and_saveexec_b64 s[22:23], vcc
	s_cbranch_execz .LBB0_383
	v_lshl_add_u64 v[18:19], v[6:7], 0, v[2:3]
	v_add_co_u32_e32 v18, vcc, 0x5000, v18
	s_nop 1
	v_addc_co_u32_e32 v19, vcc, 0, v19, vcc
	global_load_dwordx4 v[26:29], v[18:19], off offset:640 nt
	global_load_dwordx4 v[30:33], v[18:19], off offset:2688 nt
	v_add_co_u32_e32 v18, vcc, s13, v14
	s_waitcnt vmcnt(0)
	v_lshlrev_b32_e32 v42, 16, v28
	v_addc_co_u32_e32 v19, vcc, 0, v15, vcc
	v_lshl_add_u64 v[14:15], v[14:15], 0, s[8:9]
	global_load_dwordx4 v[34:37], v[18:19], off nt
	global_load_dwordx4 v[38:41], v[14:15], off offset:16 nt
	v_lshlrev_b32_e32 v14, 16, v26
	v_and_b32_e32 v15, 0xffff0000, v26
	v_lshlrev_b32_e32 v26, 16, v27
	v_and_b32_e32 v27, 0xffff0000, v27
	v_and_b32_e32 v43, 0xffff0000, v28
	v_lshlrev_b32_e32 v28, 16, v29
	v_and_b32_e32 v29, 0xffff0000, v29
	v_lshlrev_b32_e32 v18, 16, v30
	v_and_b32_e32 v19, 0xffff0000, v30
	v_lshlrev_b32_e32 v30, 16, v31
	v_and_b32_e32 v31, 0xffff0000, v31
	v_lshlrev_b32_e32 v44, 16, v32
	v_and_b32_e32 v45, 0xffff0000, v32
	v_lshlrev_b32_e32 v32, 16, v33
	v_and_b32_e32 v33, 0xffff0000, v33
	s_waitcnt vmcnt(1)
	v_pk_mul_f32 v[14:15], v[34:35], v[14:15]
	v_pk_mul_f32 v[26:27], v[36:37], v[26:27]
	s_waitcnt vmcnt(0)
	v_pk_mul_f32 v[34:35], v[38:39], v[42:43]
	v_pk_mul_f32 v[28:29], v[40:41], v[28:29]
	v_pk_fma_f32 v[8:9], v[14:15], v[18:19], v[8:9]
	v_pk_fma_f32 v[10:11], v[26:27], v[30:31], v[10:11]
	v_pk_fma_f32 v[12:13], v[34:35], v[44:45], v[12:13]
	v_pk_fma_f32 v[16:17], v[28:29], v[32:33], v[16:17]
	s_branch .LBB0_383

.LBB0_399:
	s_sleep 2
	global_load_dword v1, v0, s[4:5] sc1
	s_waitcnt vmcnt(0)
	v_cmp_gt_u32_e32 vcc, s0, v1
	s_cbranch_vccnz .LBB0_399

.LBB0_406:
	v_add_u32_e32 v189, s26, v172
	v_cmp_gt_i32_e32 vcc, s0, v189
	v_cmp_lt_i32_e64 s[2:3], s15, v189
	s_and_saveexec_b64 s[4:5], vcc
	s_cbranch_execz .LBB0_408
	v_lshl_add_u64 v[60:61], v[164:165], 0, s[8:9]
	v_lshl_add_u64 v[64:65], v[162:163], 0, s[8:9]
	v_lshl_add_u64 v[66:67], v[158:159], 0, s[8:9]
	v_lshl_add_u64 v[56:57], v[160:161], 0, s[8:9]
	global_load_dwordx2 v[170:171], v[60:61], off nt
	v_lshl_add_u64 v[60:61], v[166:167], 0, s[8:9]
	v_min_i32_e32 v88, 0x2000, v189
	global_load_dwordx4 v[56:59], v[56:57], off nt
	s_nop 0
	global_load_dwordx4 v[84:87], v[60:61], off nt
	s_nop 0
	global_load_dwordx4 v[60:63], v[64:65], off offset:-128 nt
	global_load_dwordx4 v[80:83], v[64:65], off nt
	global_load_dwordx4 v[104:107], v[64:65], off offset:128 nt
	global_load_dwordx4 v[76:79], v[66:67], off offset:-256 nt
	global_load_dwordx4 v[72:75], v[66:67], off offset:-128 nt
	global_load_dwordx4 v[68:71], v[66:67], off nt
	s_nop 0
	global_load_dwordx4 v[64:67], v[66:67], off offset:128 nt
	v_lshlrev_b32_e32 v88, 5, v88
	v_and_or_b32 v88, v88, s14, v173
	v_lshlrev_b32_e32 v88, 3, v88
	global_load_dwordx4 v[100:103], v88, s[34:35] offset:48 nt
	global_load_dwordx4 v[96:99], v88, s[34:35] offset:32 nt
	global_load_dwordx4 v[92:95], v88, s[34:35] offset:16 nt
	s_nop 0
	global_load_dwordx4 v[88:91], v88, s[34:35] nt

.LBB0_784:
	s_mov_b64 s[4:5], 0
	s_load_dword s12, s[90:91], 0xd8
	v_mbcnt_lo_u32_b32 v0, -1, 0
	v_mbcnt_hi_u32_b32 v77, -1, v0
	v_or_b32_e32 v76, s94, v77
	s_mov_b32 s0, s88
	s_add_u32 s8, s86, s4
	s_waitcnt lgkmcnt(0)
	s_mov_b32 s1, s12
	v_mov_b32_e32 v78, v76
	s_mov_b32 s13, s12
	s_addc_u32 s9, s87, s5
	s_abs_i32 s22, s13
	v_cvt_f32_u32_e32 v2, s22
	v_lshlrev_b32_e32 v0, 2, v78
	v_and_b32_e32 v84, 60, v0
	s_sub_i32 s2, 0, s22
	v_rcp_iflag_f32_e32 v0, v2
	s_mov_b32 s14, s88
	s_add_i32 s15, s14, s13
	v_mul_f32_e32 v0, 0x4f7ffffe, v0
	v_cvt_u32_f32_e32 v0, v0
	s_abs_i32 s1, s15
	s_ashr_i32 s0, s15, 31
	v_ashrrev_i32_e32 v80, 3, v78
	v_readfirstlane_b32 s23, v0
	s_mul_i32 s2, s2, s23
	s_mul_hi_u32 s2, s23, s2
	s_add_i32 s23, s23, s2
	s_mul_hi_u32 s2, s1, s23
	s_mul_i32 s2, s2, s22
	s_sub_i32 s1, s1, s2
	s_sub_i32 s2, s1, s22
	s_cmp_ge_u32 s1, s22
	s_cselect_b32 s1, s2, s1
	s_sub_i32 s2, s1, s22
	s_cmp_ge_u32 s1, s22
	s_cselect_b32 s1, s2, s1
	s_xor_b32 s1, s1, s0
	v_lshlrev_b32_e32 v2, 3, v78
	s_sub_i32 s24, s1, s0
	v_ashrrev_i32_e32 v79, 4, v78
	v_mov_b32_e32 v1, 0
	v_lshl_add_u32 v81, v84, 2, 0
	v_and_b32_e32 v82, 56, v2
	s_cmpk_lt_i32 s24, 0x480
	v_lshl_add_u32 v83, v80, 2, 0
	s_load_dword s59, s[90:91], 0xd8
	v_mbcnt_lo_u32_b32 v100, -1, 0
	v_mbcnt_hi_u32_b32 v100, -1, v100
	s_lshr_b32 s69, s94, 6
	s_lshl_b32 s82, s69, 10
	s_lshl_b32 s83, s69, 1
	s_lshr_b32 s98, s69, 2
	v_lshrrev_b32_e32 v101, 5, v100
	v_and_b32_e32 v113, 31, v100
	s_add_i32 s70, s83, 0
	v_add_u32_e32 v102, s70, v101
	s_add_i32 s70, s98, 0
	v_xor_b32_e32 v106, s70, v113
	v_lshlrev_b32_e32 v106, 4, v106
	s_add_i32 s70, s83, 16
	v_add_u32_e32 v103, s70, v101
	s_add_i32 s70, s98, 2
	v_xor_b32_e32 v107, s70, v113
	v_lshlrev_b32_e32 v107, 4, v107
	s_add_i32 s70, s83, 32
	v_add_u32_e32 v104, s70, v101
	s_add_i32 s70, s98, 4
	v_xor_b32_e32 v108, s70, v113
	v_lshlrev_b32_e32 v108, 4, v108
	s_add_i32 s70, s83, 48
	v_add_u32_e32 v105, s70, v101
	s_add_i32 s70, s98, 6
	v_xor_b32_e32 v109, s70, v113
	v_lshlrev_b32_e32 v109, 4, v109
	s_lshr_b32 s70, s94, 3
	v_lshrrev_b32_e32 v112, 3, v100
	v_add_u32_e32 v112, s70, v112
	v_and_b32_e32 v101, 7, v100
	v_lshlrev_b32_e32 v111, 4, v101
	v_lshrrev_b32_e32 v113, 2, v112
	v_xor_b32_e32 v113, v113, v101
	v_lshlrev_b32_e32 v113, 4, v113
	v_lshl_add_u32 v110, v101, 12, v113
	v_and_b32_e32 v113, 3, v112
	v_lshl_add_u32 v110, v113, 2, v110
	s_waitcnt lgkmcnt(0)
	s_mov_b32 s61, s88
	s_mov_b32 s60, s88
	s_mov_b32 s101, 7520
	s_mov_b32 s58, -2

.Lwp1_doissue:
	s_cmp_lt_u32 s60, s101
	s_cbranch_scc0 .Lwp1_noissue
	s_add_u32 s99, s58, 2
	s_and_b32 s99, s99, 3
	s_cmp_lt_u32 s60, 2272
	s_cbranch_scc0 .Lwp1_isel_m_1
	v_readlane_b32 s62, v245, 0
	v_readlane_b32 s63, v245, 1
	s_sub_u32 s65, s60, 0
	s_mov_b32 s64, 0x8d00
	s_mul_hi_u32 s66, s65, 0x39b0ad2
	s_mul_i32 s69, s66, 71
	s_sub_u32 s67, s65, s69
	s_add_u32 s62, s62, 0x4680000
	s_addc_u32 s63, s63, 0
	s_cmp_eq_u32 s67, 70
	s_cselect_b32 s68, 1, 0
	s_branch .Lwp1_isel_done_m

.LBB0_1033:
	s_or_b64 exec, exec, s[18:19]
	global_load_dwordx4 v[6:9], v[8:9], off offset:3712 nt
	v_ashrrev_i32_e32 v5, 31, v4
	v_lshlrev_b64 v[4:5], 12, v[4:5]
	v_add_u32_e32 v20, s0, v20
	v_lshl_add_u64 v[4:5], s[4:5], 0, v[4:5]
	v_cmp_lt_i32_e32 vcc, s15, v20
	v_lshl_add_u64 v[4:5], v[4:5], 0, v[2:3]
	s_or_b64 s[16:17], vcc, s[16:17]
	v_add_co_u32_e32 v18, vcc, 0x1b3b4000, v4
	v_add_u32_e32 v21, s1, v21
	s_nop 0
	v_addc_co_u32_e32 v19, vcc, 0, v5, vcc
	s_waitcnt vmcnt(0)
	v_lshlrev_b32_e32 v2, 16, v6
	v_and_b32_e32 v4, 0xffff0000, v6
	v_lshlrev_b32_e32 v5, 16, v7
	v_and_b32_e32 v6, 0xffff0000, v7
	v_lshlrev_b32_e32 v7, 16, v8
	v_and_b32_e32 v8, 0xffff0000, v8
	v_lshlrev_b32_e32 v22, 16, v9
	v_and_b32_e32 v9, 0xffff0000, v9
	v_mul_f32_e32 v4, v17, v4
	v_mul_f32_e32 v5, v12, v5
	v_mul_f32_e32 v6, v13, v6
	v_mul_f32_e32 v7, v10, v7
	v_mul_f32_e32 v2, v16, v2
	v_mul_f32_e32 v8, v11, v8
	v_mul_f32_e32 v10, v14, v22
	v_mul_f32_e32 v9, v15, v9
	v_cvt_pk_bf16_f32 v4, v2, v4
	v_cvt_pk_bf16_f32 v5, v5, v6
	v_cvt_pk_bf16_f32 v6, v7, v8
	v_cvt_pk_bf16_f32 v7, v10, v9
	global_store_dwordx4 v[18:19], v[4:7], off offset:512
	s_andn2_b64 exec, exec, s[16:17]
	s_cbranch_execz .LBB0_1038
.LBB0_1034:
	v_ashrrev_i32_e32 v4, 6, v20
	v_and_b32_e32 v10, 0x1f8, v21
	v_and_b32_e32 v5, 0xfff, v4
	v_lshlrev_b32_e32 v2, 2, v10
	v_mad_i64_i32 v[8:9], s[18:19], v4, s13, v[0:1]
	v_lshl_add_u64 v[6:7], s[6:7], 0, v[2:3]
	v_cmp_ne_u32_e32 vcc, 0, v5
	v_lshlrev_b32_e32 v2, 1, v10
	v_mov_b32_e32 v14, 0
	v_mov_b32_e32 v15, 0
	v_mov_b32_e32 v10, 0
	v_mov_b32_e32 v11, 0
	v_mov_b32_e32 v12, 0
	v_mov_b32_e32 v13, 0
	v_mov_b32_e32 v18, 0
	v_mov_b32_e32 v19, 0
	s_and_saveexec_b64 s[18:19], vcc
	s_cbranch_execz .LBB0_1036
	v_lshl_add_u64 v[10:11], v[8:9], 0, v[2:3]
	v_add_co_u32_e32 v18, vcc, 0xffffd000, v10
	s_nop 1
	v_addc_co_u32_e32 v19, vcc, -1, v11, vcc
	global_load_dwordx4 v[10:13], v[18:19], off offset:-3456 nt
	global_load_dwordx4 v[14:17], v[18:19], off offset:-1408 nt
	global_load_dwordx4 v[22:25], v[6:7], off nt
	global_load_dwordx4 v[26:29], v[6:7], off offset:16 nt
	s_waitcnt vmcnt(0)
	v_lshlrev_b32_e32 v18, 16, v10
	v_and_b32_e32 v19, 0xffff0000, v10
	v_lshlrev_b32_e32 v10, 16, v11
	v_and_b32_e32 v11, 0xffff0000, v11
	v_lshlrev_b32_e32 v32, 16, v12
	v_and_b32_e32 v33, 0xffff0000, v12
	v_lshlrev_b32_e32 v12, 16, v13
	v_and_b32_e32 v13, 0xffff0000, v13
	v_lshlrev_b32_e32 v30, 16, v14
	v_and_b32_e32 v31, 0xffff0000, v14
	v_lshlrev_b32_e32 v14, 16, v15
	v_and_b32_e32 v15, 0xffff0000, v15
	v_lshlrev_b32_e32 v34, 16, v16
	v_and_b32_e32 v35, 0xffff0000, v16
	v_lshlrev_b32_e32 v16, 16, v17
	v_and_b32_e32 v17, 0xffff0000, v17
	v_pk_mul_f32 v[18:19], v[22:23], v[18:19]
	v_pk_mul_f32 v[22:23], v[24:25], v[10:11]
	v_pk_mul_f32 v[24:25], v[26:27], v[32:33]
	v_pk_mul_f32 v[26:27], v[28:29], v[12:13]
	v_pk_fma_f32 v[10:11], v[18:19], v[30:31], 0 op_sel_hi:[1,1,0]
	v_pk_fma_f32 v[12:13], v[22:23], v[14:15], 0 op_sel_hi:[1,1,0]
	v_pk_fma_f32 v[18:19], v[24:25], v[34:35], 0 op_sel_hi:[1,1,0]
	v_pk_fma_f32 v[14:15], v[26:27], v[16:17], 0 op_sel_hi:[1,1,0]
.LBB0_1036:
	s_or_b64 exec, exec, s[18:19]
	v_lshl_add_u64 v[8:9], v[8:9], 0, v[2:3]
	v_add_co_u32_e32 v16, vcc, s14, v8
	global_load_dwordx4 v[22:25], v[8:9], off offset:2688 nt
	global_load_dwordx4 v[26:29], v[6:7], off offset:2064 nt
	global_load_dwordx4 v[30:33], v[6:7], off offset:2048 nt
	v_addc_co_u32_e32 v17, vcc, 0, v9, vcc
	global_load_dwordx4 v[34:37], v[16:17], off offset:640 nt
	v_cmp_ne_u32_e32 vcc, s12, v5
	s_waitcnt vmcnt(0)
	v_lshlrev_b32_e32 v16, 16, v22
	v_and_b32_e32 v17, 0xffff0000, v22
	v_lshlrev_b32_e32 v22, 16, v23
	v_and_b32_e32 v23, 0xffff0000, v23
	v_lshlrev_b32_e32 v38, 16, v24
	v_and_b32_e32 v39, 0xffff0000, v24
	v_lshlrev_b32_e32 v24, 16, v25
	v_and_b32_e32 v25, 0xffff0000, v25
	v_pk_mul_f32 v[16:17], v[30:31], v[16:17]
	v_pk_mul_f32 v[22:23], v[32:33], v[22:23]
	v_pk_mul_f32 v[26:27], v[26:27], v[38:39]
	v_pk_mul_f32 v[24:25], v[28:29], v[24:25]
	v_lshlrev_b32_e32 v28, 16, v34
	v_and_b32_e32 v29, 0xffff0000, v34
	v_lshlrev_b32_e32 v30, 16, v35
	v_and_b32_e32 v31, 0xffff0000, v35
	v_lshlrev_b32_e32 v32, 16, v36
	v_and_b32_e32 v33, 0xffff0000, v36
	v_lshlrev_b32_e32 v34, 16, v37
	v_and_b32_e32 v35, 0xffff0000, v37
	v_pk_fma_f32 v[16:17], v[16:17], v[28:29], v[10:11]
	v_pk_fma_f32 v[12:13], v[22:23], v[30:31], v[12:13]
	v_pk_fma_f32 v[10:11], v[26:27], v[32:33], v[18:19]
	v_pk_fma_f32 v[14:15], v[24:25], v[34:35], v[14:15]
	s_and_saveexec_b64 s[18:19], vcc
	s_cbranch_execz .LBB0_1033
	v_add_co_u32_e32 v18, vcc, 0x5000, v8
	s_nop 1
	v_addc_co_u32_e32 v19, vcc, 0, v9, vcc
	global_load_dwordx4 v[22:25], v[18:19], off offset:640 nt
	global_load_dwordx4 v[26:29], v[18:19], off offset:2688 nt
	v_add_co_u32_e32 v18, vcc, s14, v6
	s_waitcnt vmcnt(0)
	v_lshlrev_b32_e32 v38, 16, v24
	v_addc_co_u32_e32 v19, vcc, 0, v7, vcc
	v_lshl_add_u64 v[6:7], v[6:7], 0, s[8:9]
	global_load_dwordx4 v[30:33], v[18:19], off nt
	global_load_dwordx4 v[34:37], v[6:7], off offset:16 nt
	v_lshlrev_b32_e32 v6, 16, v22
	v_and_b32_e32 v7, 0xffff0000, v22
	v_lshlrev_b32_e32 v22, 16, v23
	v_and_b32_e32 v23, 0xffff0000, v23
	v_and_b32_e32 v39, 0xffff0000, v24
	v_lshlrev_b32_e32 v24, 16, v25
	v_and_b32_e32 v25, 0xffff0000, v25
	v_lshlrev_b32_e32 v18, 16, v26
	v_and_b32_e32 v19, 0xffff0000, v26
	v_lshlrev_b32_e32 v26, 16, v27
	v_and_b32_e32 v27, 0xffff0000, v27
	v_lshlrev_b32_e32 v40, 16, v28
	v_and_b32_e32 v41, 0xffff0000, v28
	v_lshlrev_b32_e32 v28, 16, v29
	v_and_b32_e32 v29, 0xffff0000, v29
	s_waitcnt vmcnt(0)
	v_pk_mul_f32 v[6:7], v[30:31], v[6:7]
	v_pk_mul_f32 v[22:23], v[32:33], v[22:23]
	v_pk_mul_f32 v[30:31], v[34:35], v[38:39]
	v_pk_mul_f32 v[24:25], v[36:37], v[24:25]
	v_pk_fma_f32 v[16:17], v[6:7], v[18:19], v[16:17]
	v_pk_fma_f32 v[12:13], v[22:23], v[26:27], v[12:13]
	v_pk_fma_f32 v[10:11], v[30:31], v[40:41], v[10:11]
	v_pk_fma_f32 v[14:15], v[24:25], v[28:29], v[14:15]
	s_branch .LBB0_1033

.LBB0_1054:
	v_add_u32_e32 v193, s18, v164
	v_cmp_gt_i32_e64 s[2:3], s0, v193
	v_cmp_lt_i32_e32 vcc, s15, v193
	s_and_saveexec_b64 s[4:5], s[2:3]
	s_cbranch_execz .LBB0_1056
	v_lshl_add_u64 v[60:61], v[168:169], 0, s[6:7]
	v_lshl_add_u64 v[64:65], v[166:167], 0, s[6:7]
	v_lshl_add_u64 v[66:67], v[160:161], 0, s[6:7]
	v_lshl_add_u64 v[56:57], v[162:163], 0, s[6:7]
	global_load_dwordx2 v[172:173], v[60:61], off nt
	v_lshl_add_u64 v[60:61], v[170:171], 0, s[6:7]
	v_min_i32_e32 v88, 0x2000, v193
	global_load_dwordx4 v[56:59], v[56:57], off nt
	s_nop 0
	global_load_dwordx4 v[84:87], v[60:61], off nt
	s_nop 0
	global_load_dwordx4 v[60:63], v[64:65], off offset:-128 nt
	global_load_dwordx4 v[80:83], v[64:65], off nt
	global_load_dwordx4 v[104:107], v[64:65], off offset:128 nt
	global_load_dwordx4 v[76:79], v[66:67], off offset:-256 nt
	global_load_dwordx4 v[72:75], v[66:67], off offset:-128 nt
	global_load_dwordx4 v[68:71], v[66:67], off nt
	s_nop 0
	global_load_dwordx4 v[64:67], v[66:67], off offset:128 nt
	v_lshlrev_b32_e32 v88, 5, v88
	v_and_or_b32 v88, v88, s14, v165
	v_lshlrev_b32_e32 v88, 3, v88
	global_load_dwordx4 v[100:103], v88, s[22:23] offset:48 nt
	global_load_dwordx4 v[96:99], v88, s[22:23] offset:32 nt
	global_load_dwordx4 v[92:95], v88, s[22:23] offset:16 nt
	s_nop 0
	global_load_dwordx4 v[88:91], v88, s[22:23] nt
